# ctx small-tile (K=2816) epilogue by hand: operand loads prefetched under the last two K tiles, row sum-of-squares by DPP + one batched bpermute round
# speedup vs baseline: 1.0099x; 1.0036x over previous
; template <int K>
; DI void gemm_small_tile(unsigned char* lds, const int tid, const u16* __restrict__ A, const u16* __restrict__ Bt,
;                         const int row0, const int col0, const SmallEpi& E) {
;     ...
;   for (int t = 0; t < NT; ++t) {
;     if (t + 4 < NT) asm volatile("s_waitcnt vmcnt(12)" ::: "memory");
;     else if (t + 3 < NT) asm volatile("s_waitcnt vmcnt(9)" ::: "memory");
;     else if (t + 2 < NT) asm volatile("s_waitcnt vmcnt(6)" ::: "memory");
;     else if (t + 1 < NT) asm volatile("s_waitcnt vmcnt(3)" ::: "memory");
;     else asm volatile("s_waitcnt vmcnt(0)" ::: "memory");
;     __builtin_amdgcn_s_barrier();
;     if (t + 5 < NT) SM_LOAD(t + 5, stl);
;     const unsigned char* st = lds + stc * 24576;
;     stc = (stc == 5) ? 0 : stc + 1; stl = (stl == 5) ? 0 : stl + 1;
; #pragma unroll
;     for (int ks = 0; ks < 4; ++ks) {
;       const bf16x8 af = *(const bf16x8*)(st + aoff + (((ks * 2 + hl) ^ swk) << 4));
;       const bf16x8 bf = *(const bf16x8*)(st + boff + (((ks * 2 + hl) ^ swk) << 4));
;       acc = __builtin_amdgcn_mfma_f32_32x32x16_bf16(af, bf, acc, 0, 0, 0);
;     }
;   }
;     ...
;   const int col = col0 + wn * 32 + ql;
;   const float gv = E.gate[col] * E.coef;
;   const float gm = E.do_next ? E.gnext[col] * (1.f + E.scnext[col]) : 0.f;
;   float hv[16];
; #pragma unroll
;   for (int i = 0; i < 16; ++i) {
;     const int row = row0 + wm * 32 + 8 * (i >> 2) + 4 * hl + (i & 3);
;     hv[i] = E.hin[(size_t)row * DM + col];
;   }
; #pragma unroll
;   for (int i = 0; i < 16; ++i) {
;     const int rloc = wm * 32 + 8 * (i >> 2) + 4 * hl + (i & 3);
;     const size_t o = (size_t)(row0 + rloc) * DM + col;
;     const float hn = hv[i] + gv * acc[i];
;     E.hout[o] = hn;
.LBB0_820:
	v_lshl_or_b32 v183, s16, 7, v29
	v_lshl_add_u32 v184, v28, 2, v42
	v_lshlrev_b32_e32 v183, 2, v183
	v_add_u32_e32 v184, s54, v184
	global_load_dword v164, v183, s[50:51]
	s_and_b64 vcc, exec, s[46:47]
	s_cbranch_vccz .Lsm_pf_nonext
	global_load_dword v165, v183, s[48:49]
	global_load_dword v166, v183, s[42:43]
	s_branch .Lsm_pf_join
.Lsm_pf_nonext:
	global_load_dword v165, v183, s[50:51]
	global_load_dword v166, v183, s[50:51]
.Lsm_pf_join:
	v_lshl_add_u32 v184, v184, 12, v183
	global_load_dword v167, v184, s[0:1]
	v_add_u32_e32 v186, 0x1000, v184
	global_load_dword v168, v186, s[0:1]
	v_add_u32_e32 v187, 0x2000, v184
	global_load_dword v169, v187, s[0:1]
	v_add_u32_e32 v185, 0x3000, v184
	global_load_dword v170, v185, s[0:1]
	v_add_u32_e32 v186, 0x8000, v184
	global_load_dword v171, v186, s[0:1]
	v_add_u32_e32 v187, 0x9000, v184
	global_load_dword v172, v187, s[0:1]
	v_add_u32_e32 v185, 0xa000, v184
	global_load_dword v173, v185, s[0:1]
	v_add_u32_e32 v186, 0xb000, v184
	global_load_dword v174, v186, s[0:1]
	v_add_u32_e32 v187, 0x10000, v184
	global_load_dword v175, v187, s[0:1]
	v_add_u32_e32 v185, 0x11000, v184
	global_load_dword v176, v185, s[0:1]
	v_add_u32_e32 v186, 0x12000, v184
	global_load_dword v177, v186, s[0:1]
	v_add_u32_e32 v187, 0x13000, v184
	global_load_dword v178, v187, s[0:1]
	v_add_u32_e32 v185, 0x18000, v184
	global_load_dword v179, v185, s[0:1]
	v_add_u32_e32 v186, 0x19000, v184
	global_load_dword v180, v186, s[0:1]
	v_add_u32_e32 v187, 0x1a000, v184
	global_load_dword v181, v187, s[0:1]
	v_add_u32_e32 v185, 0x1b000, v184
	global_load_dword v182, v185, s[0:1]
	s_mul_i32 s2, s19, 0x6000
	s_add_i32 s2, s2, 0
	v_add_u32_e32 v0, s2, v34
	v_add_u32_e32 v18, v0, v35
	s_waitcnt vmcnt(22)
	s_barrier
	ds_read_b128 v[18:21], v18
	v_add_u32_e32 v30, s2, v36
	v_add_u32_e32 v22, v30, v35
	ds_read_b128 v[22:25], v22 offset:8192
	s_and_b64 vcc, exec, s[46:47]
	s_waitcnt lgkmcnt(0)
	v_mfma_f32_32x32x16_bf16 v[2:17], v[18:21], v[22:25], v[2:17]
	v_add_u32_e32 v18, v0, v33
	ds_read_b128 v[18:21], v18
	v_add_u32_e32 v22, v30, v33
	ds_read_b128 v[22:25], v22 offset:8192
	s_waitcnt lgkmcnt(0)
	v_mfma_f32_32x32x16_bf16 v[2:17], v[18:21], v[22:25], v[2:17]
	v_add_u32_e32 v18, v0, v32
	ds_read_b128 v[18:21], v18
	v_add_u32_e32 v22, v30, v32
	ds_read_b128 v[22:25], v22 offset:8192
	v_add_u32_e32 v0, v0, v31
	s_waitcnt lgkmcnt(0)
	v_mfma_f32_32x32x16_bf16 v[2:17], v[18:21], v[22:25], v[2:17]
	ds_read_b128 v[18:21], v0
	v_add_u32_e32 v0, v30, v31
	ds_read_b128 v[22:25], v0 offset:8192
	v_add_u32_e32 v0, 0, v34
	s_waitcnt vmcnt(19)
	s_barrier
	v_add_u32_e32 v30, 0, v36
	s_waitcnt lgkmcnt(0)
	v_mfma_f32_32x32x16_bf16 v[2:17], v[18:21], v[22:25], v[2:17]
	v_add_u32_e32 v18, v0, v35
	ds_read_b128 v[18:21], v18 offset:24576
	v_add_u32_e32 v22, v30, v35
	ds_read_b128 v[22:25], v22 offset:32768
	s_waitcnt lgkmcnt(0)
	v_mfma_f32_32x32x16_bf16 v[2:17], v[18:21], v[22:25], v[2:17]
	v_add_u32_e32 v18, v0, v33
	ds_read_b128 v[18:21], v18 offset:24576
	v_add_u32_e32 v22, v30, v33
	ds_read_b128 v[22:25], v22 offset:32768
	s_waitcnt lgkmcnt(0)
	v_mfma_f32_32x32x16_bf16 v[2:17], v[18:21], v[22:25], v[2:17]
	v_add_u32_e32 v18, v0, v32
	ds_read_b128 v[18:21], v18 offset:24576
	v_add_u32_e32 v22, v30, v32
	ds_read_b128 v[22:25], v22 offset:32768
	v_add_u32_e32 v0, v0, v31
	s_waitcnt lgkmcnt(0)
	v_mfma_f32_32x32x16_bf16 v[2:17], v[18:21], v[22:25], v[2:17]
	ds_read_b128 v[18:21], v0 offset:24576
	v_add_u32_e32 v0, v30, v31
	ds_read_b128 v[22:25], v0 offset:32768
	s_waitcnt lgkmcnt(0)
	v_mfma_f32_32x32x16_bf16 v[2:17], v[18:21], v[22:25], v[2:17]
	s_and_b64 vcc, exec, s[46:47]
	s_cbranch_vccz .Lsm_ep_old
	v_readlane_b32 s2, v254, 59
	v_readlane_b32 s3, v254, 60
	v_lshlrev_b32_e32 v185, 2, v27
	v_lshl_add_u32 v187, v28, 2, v42
	v_xor_b32_e32 v186, 64, v185
	v_lshl_add_u32 v187, v41, 6, v187
	v_lshlrev_b32_e32 v187, 2, v187
	v_add_u32_e32 v187, 0x24040, v187
	s_waitcnt vmcnt(0)
	s_nop 15
	v_mul_f32_e32 v22, v160, v164
	v_add_f32_e32 v165, 1.0, v165
	v_mul_f32_e32 v21, v166, v165
	v_fmac_f32_e32 v167, v2, v22
	v_fmac_f32_e32 v168, v3, v22
	v_fmac_f32_e32 v169, v4, v22
	v_fmac_f32_e32 v170, v5, v22
	v_fmac_f32_e32 v171, v6, v22
	v_fmac_f32_e32 v172, v7, v22
	v_fmac_f32_e32 v173, v8, v22
	v_fmac_f32_e32 v174, v9, v22
	v_fmac_f32_e32 v175, v10, v22
	v_fmac_f32_e32 v176, v11, v22
	v_fmac_f32_e32 v177, v12, v22
	v_fmac_f32_e32 v178, v13, v22
	v_fmac_f32_e32 v179, v14, v22
	v_fmac_f32_e32 v180, v15, v22
	v_fmac_f32_e32 v181, v16, v22
	v_fmac_f32_e32 v182, v17, v22
	v_mov_b32_e32 v188, v184
	v_mul_f32_e32 v189, v21, v167
	global_store_dword v188, v167, s[44:45]
	v_lshrrev_b32_e32 v190, 1, v188
	v_cvt_pk_bf16_f32 v189, v189, v189
	v_mul_f32_e32 v2, v167, v167
	global_store_short v190, v189, s[2:3]
	v_add_u32_e32 v191, 0x1000, v184
	v_mul_f32_e32 v192, v21, v168
	global_store_dword v191, v168, s[44:45]
	v_lshrrev_b32_e32 v193, 1, v191
	v_cvt_pk_bf16_f32 v192, v192, v192
	v_mul_f32_e32 v3, v168, v168
	global_store_short v193, v192, s[2:3]
	v_add_u32_e32 v188, 0x2000, v184
	v_mul_f32_e32 v189, v21, v169
	global_store_dword v188, v169, s[44:45]
	v_lshrrev_b32_e32 v190, 1, v188
	v_cvt_pk_bf16_f32 v189, v189, v189
	v_mul_f32_e32 v4, v169, v169
	global_store_short v190, v189, s[2:3]
	v_add_u32_e32 v191, 0x3000, v184
	v_mul_f32_e32 v192, v21, v170
	global_store_dword v191, v170, s[44:45]
	v_lshrrev_b32_e32 v193, 1, v191
	v_cvt_pk_bf16_f32 v192, v192, v192
	v_mul_f32_e32 v5, v170, v170
	global_store_short v193, v192, s[2:3]
	v_add_u32_e32 v188, 0x8000, v184
	v_mul_f32_e32 v189, v21, v171
	global_store_dword v188, v171, s[44:45]
	v_lshrrev_b32_e32 v190, 1, v188
; DI float shx(float v, int mask, int lane) { return __int_as_float(__builtin_amdgcn_ds_bpermute((lane ^ mask) << 2, __float_as_int(v))); }
; DI u16 f2bf(float a) { return (u16)(pk2(a, 0.f) & 0xffffu); }
; template <int K>
; DI void gemm_small_tile(unsigned char* lds, const int tid, const u16* __restrict__ A, const u16* __restrict__ Bt,
;                         const int row0, const int col0, const SmallEpi& E) {
;     ...
;   for (int i = 0; i < 16; ++i) {
;     const int rloc = wm * 32 + 8 * (i >> 2) + 4 * hl + (i & 3);
;     const size_t o = (size_t)(row0 + rloc) * DM + col;
;     const float hn = hv[i] + gv * acc[i];
;     E.hout[o] = hn;
;     if (E.do_next) {
;       E.hg[o] = f2bf(hn * gm);
;       float sq = hn * hn;
;       sq += shx(sq, 1, lane); sq += shx(sq, 2, lane); sq += shx(sq, 4, lane); sq += shx(sq, 8, lane); sq += shx(sq, 16, lane);
	v_cvt_pk_bf16_f32 v189, v189, v189
	v_mul_f32_e32 v6, v171, v171
	global_store_short v190, v189, s[2:3]
	v_add_u32_e32 v191, 0x9000, v184
	v_mul_f32_e32 v192, v21, v172
	global_store_dword v191, v172, s[44:45]
	v_lshrrev_b32_e32 v193, 1, v191
	v_cvt_pk_bf16_f32 v192, v192, v192
	v_mul_f32_e32 v7, v172, v172
	global_store_short v193, v192, s[2:3]
	v_add_u32_e32 v188, 0xa000, v184
	v_mul_f32_e32 v189, v21, v173
	global_store_dword v188, v173, s[44:45]
	v_lshrrev_b32_e32 v190, 1, v188
	v_cvt_pk_bf16_f32 v189, v189, v189
	v_mul_f32_e32 v8, v173, v173
	global_store_short v190, v189, s[2:3]
	v_add_u32_e32 v191, 0xb000, v184
	v_mul_f32_e32 v192, v21, v174
	global_store_dword v191, v174, s[44:45]
	v_lshrrev_b32_e32 v193, 1, v191
	v_cvt_pk_bf16_f32 v192, v192, v192
	v_mul_f32_e32 v9, v174, v174
	global_store_short v193, v192, s[2:3]
	v_add_u32_e32 v188, 0x10000, v184
	v_mul_f32_e32 v189, v21, v175
	global_store_dword v188, v175, s[44:45]
	v_lshrrev_b32_e32 v190, 1, v188
	v_cvt_pk_bf16_f32 v189, v189, v189
	v_mul_f32_e32 v10, v175, v175
	global_store_short v190, v189, s[2:3]
	v_add_u32_e32 v191, 0x11000, v184
	v_mul_f32_e32 v192, v21, v176
	global_store_dword v191, v176, s[44:45]
	v_lshrrev_b32_e32 v193, 1, v191
	v_cvt_pk_bf16_f32 v192, v192, v192
	v_mul_f32_e32 v11, v176, v176
	global_store_short v193, v192, s[2:3]
	v_add_u32_e32 v188, 0x12000, v184
	v_mul_f32_e32 v189, v21, v177
	global_store_dword v188, v177, s[44:45]
	v_lshrrev_b32_e32 v190, 1, v188
	v_cvt_pk_bf16_f32 v189, v189, v189
	v_mul_f32_e32 v12, v177, v177
	global_store_short v190, v189, s[2:3]
	v_add_u32_e32 v191, 0x13000, v184
	v_mul_f32_e32 v192, v21, v178
	global_store_dword v191, v178, s[44:45]
	v_lshrrev_b32_e32 v193, 1, v191
	v_cvt_pk_bf16_f32 v192, v192, v192
	v_mul_f32_e32 v13, v178, v178
	global_store_short v193, v192, s[2:3]
	v_add_u32_e32 v188, 0x18000, v184
	v_mul_f32_e32 v189, v21, v179
	global_store_dword v188, v179, s[44:45]
	v_lshrrev_b32_e32 v190, 1, v188
	v_cvt_pk_bf16_f32 v189, v189, v189
	v_mul_f32_e32 v14, v179, v179
	global_store_short v190, v189, s[2:3]
	v_add_u32_e32 v191, 0x19000, v184
	v_mul_f32_e32 v192, v21, v180
	global_store_dword v191, v180, s[44:45]
	v_lshrrev_b32_e32 v193, 1, v191
	v_cvt_pk_bf16_f32 v192, v192, v192
	v_mul_f32_e32 v15, v180, v180
	global_store_short v193, v192, s[2:3]
	v_add_u32_e32 v188, 0x1a000, v184
	v_mul_f32_e32 v189, v21, v181
	global_store_dword v188, v181, s[44:45]
	v_lshrrev_b32_e32 v190, 1, v188
	v_cvt_pk_bf16_f32 v189, v189, v189
	v_mul_f32_e32 v16, v181, v181
	global_store_short v190, v189, s[2:3]
	v_add_u32_e32 v191, 0x1b000, v184
	v_mul_f32_e32 v192, v21, v182
	global_store_dword v191, v182, s[44:45]
	v_lshrrev_b32_e32 v193, 1, v191
	v_cvt_pk_bf16_f32 v192, v192, v192
	v_mul_f32_e32 v17, v182, v182
	global_store_short v193, v192, s[2:3]
	v_add_f32_dpp v2, v2, v2 quad_perm:[1,0,3,2] row_mask:0xf bank_mask:0xf
	v_add_f32_dpp v3, v3, v3 quad_perm:[1,0,3,2] row_mask:0xf bank_mask:0xf
	v_add_f32_dpp v4, v4, v4 quad_perm:[1,0,3,2] row_mask:0xf bank_mask:0xf
	v_add_f32_dpp v5, v5, v5 quad_perm:[1,0,3,2] row_mask:0xf bank_mask:0xf
	v_add_f32_dpp v6, v6, v6 quad_perm:[1,0,3,2] row_mask:0xf bank_mask:0xf
	v_add_f32_dpp v7, v7, v7 quad_perm:[1,0,3,2] row_mask:0xf bank_mask:0xf
	v_add_f32_dpp v8, v8, v8 quad_perm:[1,0,3,2] row_mask:0xf bank_mask:0xf
	v_add_f32_dpp v9, v9, v9 quad_perm:[1,0,3,2] row_mask:0xf bank_mask:0xf
	v_add_f32_dpp v10, v10, v10 quad_perm:[1,0,3,2] row_mask:0xf bank_mask:0xf
	v_add_f32_dpp v11, v11, v11 quad_perm:[1,0,3,2] row_mask:0xf bank_mask:0xf
	v_add_f32_dpp v12, v12, v12 quad_perm:[1,0,3,2] row_mask:0xf bank_mask:0xf
	v_add_f32_dpp v13, v13, v13 quad_perm:[1,0,3,2] row_mask:0xf bank_mask:0xf
	v_add_f32_dpp v14, v14, v14 quad_perm:[1,0,3,2] row_mask:0xf bank_mask:0xf
	v_add_f32_dpp v15, v15, v15 quad_perm:[1,0,3,2] row_mask:0xf bank_mask:0xf
	v_add_f32_dpp v16, v16, v16 quad_perm:[1,0,3,2] row_mask:0xf bank_mask:0xf
	v_add_f32_dpp v17, v17, v17 quad_perm:[1,0,3,2] row_mask:0xf bank_mask:0xf
	v_add_f32_dpp v2, v2, v2 quad_perm:[2,3,0,1] row_mask:0xf bank_mask:0xf
	v_add_f32_dpp v3, v3, v3 quad_perm:[2,3,0,1] row_mask:0xf bank_mask:0xf
	v_add_f32_dpp v4, v4, v4 quad_perm:[2,3,0,1] row_mask:0xf bank_mask:0xf
	v_add_f32_dpp v5, v5, v5 quad_perm:[2,3,0,1] row_mask:0xf bank_mask:0xf
	v_add_f32_dpp v6, v6, v6 quad_perm:[2,3,0,1] row_mask:0xf bank_mask:0xf
	v_add_f32_dpp v7, v7, v7 quad_perm:[2,3,0,1] row_mask:0xf bank_mask:0xf
	v_add_f32_dpp v8, v8, v8 quad_perm:[2,3,0,1] row_mask:0xf bank_mask:0xf
	v_add_f32_dpp v9, v9, v9 quad_perm:[2,3,0,1] row_mask:0xf bank_mask:0xf
	v_add_f32_dpp v10, v10, v10 quad_perm:[2,3,0,1] row_mask:0xf bank_mask:0xf
; DI float shx(float v, int mask, int lane) { return __int_as_float(__builtin_amdgcn_ds_bpermute((lane ^ mask) << 2, __float_as_int(v))); }
; template <int K>
; DI void gemm_small_tile(unsigned char* lds, const int tid, const u16* __restrict__ A, const u16* __restrict__ Bt,
;                         const int row0, const int col0, const SmallEpi& E) {
;     ...
;       sq += shx(sq, 1, lane); sq += shx(sq, 2, lane); sq += shx(sq, 4, lane); sq += shx(sq, 8, lane); sq += shx(sq, 16, lane);
;       if (ql == 0) E.ssl[wn * 64 + rloc] = sq;
;     }
;   }
;   if (E.do_next) {
;     __syncthreads();
;     if (tid < 64) E.sspc[(size_t)(row0 - M_LAT + tid) * 8 + (col0 >> 7)] = (E.ssl[tid] + E.ssl[64 + tid]) + (E.ssl[128 + tid] + E.ssl[192 + tid]);
	v_add_f32_dpp v11, v11, v11 quad_perm:[2,3,0,1] row_mask:0xf bank_mask:0xf
	v_add_f32_dpp v12, v12, v12 quad_perm:[2,3,0,1] row_mask:0xf bank_mask:0xf
	v_add_f32_dpp v13, v13, v13 quad_perm:[2,3,0,1] row_mask:0xf bank_mask:0xf
	v_add_f32_dpp v14, v14, v14 quad_perm:[2,3,0,1] row_mask:0xf bank_mask:0xf
	v_add_f32_dpp v15, v15, v15 quad_perm:[2,3,0,1] row_mask:0xf bank_mask:0xf
	v_add_f32_dpp v16, v16, v16 quad_perm:[2,3,0,1] row_mask:0xf bank_mask:0xf
	v_add_f32_dpp v17, v17, v17 quad_perm:[2,3,0,1] row_mask:0xf bank_mask:0xf
	v_add_f32_dpp v2, v2, v2 row_half_mirror row_mask:0xf bank_mask:0xf
	v_add_f32_dpp v3, v3, v3 row_half_mirror row_mask:0xf bank_mask:0xf
	v_add_f32_dpp v4, v4, v4 row_half_mirror row_mask:0xf bank_mask:0xf
	v_add_f32_dpp v5, v5, v5 row_half_mirror row_mask:0xf bank_mask:0xf
	v_add_f32_dpp v6, v6, v6 row_half_mirror row_mask:0xf bank_mask:0xf
	v_add_f32_dpp v7, v7, v7 row_half_mirror row_mask:0xf bank_mask:0xf
	v_add_f32_dpp v8, v8, v8 row_half_mirror row_mask:0xf bank_mask:0xf
	v_add_f32_dpp v9, v9, v9 row_half_mirror row_mask:0xf bank_mask:0xf
	v_add_f32_dpp v10, v10, v10 row_half_mirror row_mask:0xf bank_mask:0xf
	v_add_f32_dpp v11, v11, v11 row_half_mirror row_mask:0xf bank_mask:0xf
	v_add_f32_dpp v12, v12, v12 row_half_mirror row_mask:0xf bank_mask:0xf
	v_add_f32_dpp v13, v13, v13 row_half_mirror row_mask:0xf bank_mask:0xf
	v_add_f32_dpp v14, v14, v14 row_half_mirror row_mask:0xf bank_mask:0xf
	v_add_f32_dpp v15, v15, v15 row_half_mirror row_mask:0xf bank_mask:0xf
	v_add_f32_dpp v16, v16, v16 row_half_mirror row_mask:0xf bank_mask:0xf
	v_add_f32_dpp v17, v17, v17 row_half_mirror row_mask:0xf bank_mask:0xf
	v_add_f32_dpp v2, v2, v2 row_mirror row_mask:0xf bank_mask:0xf
	v_add_f32_dpp v3, v3, v3 row_mirror row_mask:0xf bank_mask:0xf
	v_add_f32_dpp v4, v4, v4 row_mirror row_mask:0xf bank_mask:0xf
	v_add_f32_dpp v5, v5, v5 row_mirror row_mask:0xf bank_mask:0xf
	v_add_f32_dpp v6, v6, v6 row_mirror row_mask:0xf bank_mask:0xf
	v_add_f32_dpp v7, v7, v7 row_mirror row_mask:0xf bank_mask:0xf
	v_add_f32_dpp v8, v8, v8 row_mirror row_mask:0xf bank_mask:0xf
	v_add_f32_dpp v9, v9, v9 row_mirror row_mask:0xf bank_mask:0xf
	v_add_f32_dpp v10, v10, v10 row_mirror row_mask:0xf bank_mask:0xf
	v_add_f32_dpp v11, v11, v11 row_mirror row_mask:0xf bank_mask:0xf
	v_add_f32_dpp v12, v12, v12 row_mirror row_mask:0xf bank_mask:0xf
	v_add_f32_dpp v13, v13, v13 row_mirror row_mask:0xf bank_mask:0xf
	v_add_f32_dpp v14, v14, v14 row_mirror row_mask:0xf bank_mask:0xf
	v_add_f32_dpp v15, v15, v15 row_mirror row_mask:0xf bank_mask:0xf
	v_add_f32_dpp v16, v16, v16 row_mirror row_mask:0xf bank_mask:0xf
	v_add_f32_dpp v17, v17, v17 row_mirror row_mask:0xf bank_mask:0xf
	s_nop 1
	ds_bpermute_b32 v43, v186, v2
	ds_bpermute_b32 v44, v186, v3
	ds_bpermute_b32 v45, v186, v4
	ds_bpermute_b32 v46, v186, v5
	ds_bpermute_b32 v47, v186, v6
	ds_bpermute_b32 v48, v186, v7
	ds_bpermute_b32 v49, v186, v8
	ds_bpermute_b32 v50, v186, v9
	ds_bpermute_b32 v51, v186, v10
	ds_bpermute_b32 v52, v186, v11
	ds_bpermute_b32 v53, v186, v12
	ds_bpermute_b32 v54, v186, v13
	ds_bpermute_b32 v55, v186, v14
	ds_bpermute_b32 v56, v186, v15
	ds_bpermute_b32 v57, v186, v16
	s_waitcnt lgkmcnt(7)
	ds_bpermute_b32 v58, v186, v17
	v_add_f32_e32 v2, v2, v43
	v_add_f32_e32 v3, v3, v44
	v_add_f32_e32 v4, v4, v45
	v_add_f32_e32 v5, v5, v46
	v_add_f32_e32 v6, v6, v47
	v_add_f32_e32 v7, v7, v48
	v_add_f32_e32 v8, v8, v49
	v_add_f32_e32 v9, v9, v50
	s_waitcnt lgkmcnt(0)
	v_add_f32_e32 v10, v10, v51
	v_add_f32_e32 v11, v11, v52
	v_add_f32_e32 v12, v12, v53
	v_add_f32_e32 v13, v13, v54
	v_add_f32_e32 v14, v14, v55
	v_add_f32_e32 v15, v15, v56
	v_add_f32_e32 v16, v16, v57
	v_add_f32_e32 v17, v17, v58
	v_cmp_eq_u32_e32 vcc, 0, v40
	s_and_saveexec_b64 s[4:5], vcc
	ds_write_b32 v187, v2
	ds_write_b32 v187, v3 offset:4
	ds_write_b32 v187, v4 offset:8
	ds_write_b32 v187, v5 offset:12
	ds_write_b32 v187, v6 offset:32
	ds_write_b32 v187, v7 offset:36
	ds_write_b32 v187, v8 offset:40
	ds_write_b32 v187, v9 offset:44
	ds_write_b32 v187, v10 offset:64
	ds_write_b32 v187, v11 offset:68
	ds_write_b32 v187, v12 offset:72
	ds_write_b32 v187, v13 offset:76
	ds_write_b32 v187, v14 offset:96
	ds_write_b32 v187, v15 offset:100
	ds_write_b32 v187, v16 offset:104
	ds_write_b32 v187, v17 offset:108
	s_mov_b64 exec, s[4:5]
	s_mov_b64 s[2:3], exec
	s_mov_b64 s[4:5], 0
	s_branch .LBB0_891
.Lsm_ep_old:
	v_lshl_or_b32 v20, s16, 7, v29
	v_lshlrev_b32_e32 v0, 2, v20
	global_load_dword v18, v0, s[50:51]
	v_mov_b32_e32 v21, 0
	s_cbranch_vccz .LBB0_822
	global_load_dword v19, v0, s[48:49]
	global_load_dword v21, v0, s[42:43]
	s_waitcnt vmcnt(0)
	v_add_f32_e32 v19, 1.0, v19
	v_mul_f32_e32 v21, v21, v19
